# v78: pooling - next 4-token step's 12 row loads issued a third into the current step (rotated prefetch), step 0's loads in the head
# speedup vs baseline: 1.0032x; 1.0009x over previous
.LBB0_612:
	s_ashr_i32 s1, s0, 31
	s_lshl_b64 s[10:11], s[0:1], 10
	s_add_u32 s10, s34, s10
	s_addc_u32 s11, s35, s11
	s_bfe_u32 s16, s0, 0x90004
	s_and_b32 s17, s0, 0xffffe000
	s_lshl_b32 s1, s16, 4
	s_mul_i32 s16, s16, 0x1a000
	s_mul_hi_i32 s18, s17, 0x1a00
	s_mulk_i32 s17, 0x1a00
	s_add_u32 s16, s16, s17
	s_addc_u32 s17, 0, s18
	s_add_u32 s16, s34, s16
	s_addc_u32 s17, s35, s17
	s_lshl_b32 s18, s8, 4
	s_and_b32 s20, s18, 0x1ff0
	v_sub_u32_e32 v0, s20, v200
	s_and_b32 s21, s18, 0xffffe000
	v_mad_i64_i32 v[144:145], vcc, s21, v207, v[170:171]
	v_mov_b32_e32 v141, s20
	v_mov_b32_e32 v143, 0
	v_add_u32_e32 v140, 0, v0
	v_cmp_gt_u32_e32 vcc, s37, v140
	s_nop 1
	v_cndmask_b32_e32 v140, v141, v140, vcc
	v_mul_i32_i24_e32 v142, 0xd00, v140
	v_lshl_add_u64 v[146:147], v[142:143], 1, v[144:145]
	global_load_dwordx4 v[76:79], v[146:147], off offset:1536
	v_add_u32_e32 v140, 1, v0
	v_cmp_gt_u32_e32 vcc, s37, v140
	s_nop 1
	v_cndmask_b32_e32 v140, v141, v140, vcc
	v_mul_i32_i24_e32 v142, 0xd00, v140
	v_lshl_add_u64 v[146:147], v[142:143], 1, v[144:145]
	global_load_dwordx4 v[80:83], v[146:147], off offset:1536
	v_add_u32_e32 v140, 2, v0
	v_cmp_gt_u32_e32 vcc, s37, v140
	s_and_b64 vcc, s[38:39], vcc
	s_nop 1
	v_cndmask_b32_e32 v140, v141, v140, vcc
	v_mul_i32_i24_e32 v142, 0xd00, v140
	v_lshl_add_u64 v[146:147], v[142:143], 1, v[144:145]
	global_load_dwordx4 v[84:87], v[146:147], off offset:1536
	v_add_u32_e32 v140, 3, v0
	v_cmp_gt_u32_e32 vcc, s37, v140
	s_and_b64 vcc, s[38:39], vcc
	s_nop 1
	v_cndmask_b32_e32 v140, v141, v140, vcc
	v_mul_i32_i24_e32 v142, 0xd00, v140
	v_lshl_add_u64 v[146:147], v[142:143], 1, v[144:145]
	global_load_dwordx4 v[88:91], v[146:147], off offset:1536
	v_add_u32_e32 v140, 4, v0
	v_cmp_gt_u32_e32 vcc, s37, v140
	s_and_b64 vcc, s[40:41], vcc
	s_nop 1
	v_cndmask_b32_e32 v140, v141, v140, vcc
	v_mul_i32_i24_e32 v142, 0xd00, v140
	v_lshl_add_u64 v[146:147], v[142:143], 1, v[144:145]
	global_load_dwordx4 v[92:95], v[146:147], off offset:1536
	v_add_u32_e32 v140, 5, v0
	v_cmp_gt_u32_e32 vcc, s37, v140
	s_and_b64 vcc, s[40:41], vcc
	s_nop 1
	v_cndmask_b32_e32 v140, v141, v140, vcc
	v_mul_i32_i24_e32 v142, 0xd00, v140
	v_lshl_add_u64 v[146:147], v[142:143], 1, v[144:145]
	global_load_dwordx4 v[96:99], v[146:147], off offset:1536
	v_add_u32_e32 v140, 6, v0
	v_cmp_gt_u32_e32 vcc, s37, v140
	s_and_b64 vcc, s[40:41], vcc
	s_nop 1
	v_cndmask_b32_e32 v140, v141, v140, vcc
	v_mul_i32_i24_e32 v142, 0xd00, v140
	v_lshl_add_u64 v[146:147], v[142:143], 1, v[144:145]
	global_load_dwordx4 v[100:103], v[146:147], off offset:1536
	v_add_u32_e32 v140, 7, v0
	v_cmp_gt_u32_e32 vcc, s37, v140
	s_and_b64 vcc, s[40:41], vcc
	s_nop 1
	v_cndmask_b32_e32 v140, v141, v140, vcc
	v_mul_i32_i24_e32 v142, 0xd00, v140
	v_lshl_add_u64 v[146:147], v[142:143], 1, v[144:145]
	global_load_dwordx4 v[104:107], v[146:147], off offset:1536
	v_add_u32_e32 v140, 8, v0
	v_cndmask_b32_e64 v140, v141, v140, s[42:43]
	v_mul_i32_i24_e32 v142, 0xd00, v140
	v_lshl_add_u64 v[146:147], v[142:143], 1, v[144:145]
	global_load_dwordx4 v[108:111], v[146:147], off offset:1536
	v_add_u32_e32 v140, 9, v0
	v_cndmask_b32_e64 v140, v141, v140, s[42:43]
	v_mul_i32_i24_e32 v142, 0xd00, v140
	v_lshl_add_u64 v[146:147], v[142:143], 1, v[144:145]
	global_load_dwordx4 v[112:115], v[146:147], off offset:1536
	v_add_u32_e32 v140, 10, v0
	v_cndmask_b32_e64 v140, v141, v140, s[42:43]
	v_mul_i32_i24_e32 v142, 0xd00, v140
	v_lshl_add_u64 v[146:147], v[142:143], 1, v[144:145]
	global_load_dwordx4 v[116:119], v[146:147], off offset:1536
	v_add_u32_e32 v140, 11, v0
	v_cndmask_b32_e64 v140, v141, v140, s[42:43]
	v_mul_i32_i24_e32 v142, 0xd00, v140
	v_lshl_add_u64 v[146:147], v[142:143], 1, v[144:145]
	global_load_dwordx4 v[120:123], v[146:147], off offset:1536
	v_add_u32_e32 v140, 12, v0
	v_cndmask_b32_e64 v140, v141, v140, s[42:43]
	v_mul_i32_i24_e32 v142, 0xd00, v140
	v_lshl_add_u64 v[146:147], v[142:143], 1, v[144:145]
	global_load_dwordx4 v[124:127], v[146:147], off offset:1536
	v_add_u32_e32 v140, 13, v0
	v_cndmask_b32_e64 v140, v141, v140, s[42:43]
	v_mul_i32_i24_e32 v142, 0xd00, v140
	v_lshl_add_u64 v[146:147], v[142:143], 1, v[144:145]
	global_load_dwordx4 v[128:131], v[146:147], off offset:1536
	v_add_u32_e32 v140, 14, v0
	v_cndmask_b32_e64 v140, v141, v140, s[42:43]
	v_mul_i32_i24_e32 v142, 0xd00, v140
	v_lshl_add_u64 v[146:147], v[142:143], 1, v[144:145]
	global_load_dwordx4 v[132:135], v[146:147], off offset:1536
	v_add_u32_e32 v140, 15, v0
	v_cndmask_b32_e64 v140, v141, v140, s[42:43]
	v_mul_i32_i24_e32 v142, 0xd00, v140
	v_lshl_add_u64 v[146:147], v[142:143], 1, v[144:145]
	global_load_dwordx4 v[136:139], v[146:147], off offset:1536
	s_waitcnt vmcnt(0)
	v_cmp_gt_u32_e32 vcc, s37, v0
	v_mov_b32_e32 v1, s20
	s_and_b32 s19, s18, 0xffffe000
	v_cndmask_b32_e32 v2, v1, v0, vcc
	v_mad_i64_i32 v[16:17], s[18:19], s19, v207, v[170:171]
	v_mul_i32_i24_e32 v152, 0xd00, v2
	v_lshl_add_u64 v[2:3], v[152:153], 1, v[16:17]
	v_mov_b32_e32 v2, v76
	v_mov_b32_e32 v3, v77
	v_mov_b32_e32 v4, v78
	v_mov_b32_e32 v5, v79
	v_or_b32_e32 v38, s1, v200
	v_add_u32_e32 v39, s1, v201
	s_mov_b32 s18, -4
	s_waitcnt vmcnt(0)
	v_cndmask_b32_e32 v8, 0, v2, vcc
	v_add_u32_e32 v2, 1, v0
	v_cndmask_b32_e32 v12, 0, v5, vcc
	v_cndmask_b32_e32 v6, 0, v4, vcc
	v_cndmask_b32_e32 v7, 0, v3, vcc
	v_cmp_gt_u32_e32 vcc, s37, v2
	s_nop 1
	v_cndmask_b32_e32 v2, v1, v2, vcc
	v_mul_i32_i24_e32 v152, 0xd00, v2
	v_lshl_add_u64 v[2:3], v[152:153], 1, v[16:17]
	v_mov_b32_e32 v2, v80
	v_mov_b32_e32 v3, v81
	v_mov_b32_e32 v4, v82
	v_mov_b32_e32 v5, v83
	s_waitcnt vmcnt(0)
	v_cndmask_b32_e32 v10, 0, v2, vcc
	v_add_u32_e32 v2, 2, v0
	v_cndmask_b32_e32 v13, 0, v5, vcc
	v_cndmask_b32_e32 v14, 0, v4, vcc
	v_cndmask_b32_e32 v9, 0, v3, vcc
	v_cmp_gt_u32_e32 vcc, s37, v2
	s_and_b64 vcc, s[38:39], vcc
	s_nop 0
	v_cndmask_b32_e32 v2, v1, v2, vcc
	v_mul_i32_i24_e32 v152, 0xd00, v2
	v_lshl_add_u64 v[2:3], v[152:153], 1, v[16:17]
	v_mov_b32_e32 v2, v84
	v_mov_b32_e32 v3, v85
	v_mov_b32_e32 v4, v86
	v_mov_b32_e32 v5, v87
	s_waitcnt vmcnt(0)
	v_cndmask_b32_e32 v11, 0, v2, vcc
	v_add_u32_e32 v2, 3, v0
	v_cndmask_b32_e32 v15, 0, v5, vcc
	v_cndmask_b32_e32 v18, 0, v4, vcc
	v_cndmask_b32_e32 v19, 0, v3, vcc
	v_cmp_gt_u32_e32 vcc, s37, v2
	s_and_b64 vcc, s[38:39], vcc
	s_nop 0
	v_cndmask_b32_e32 v2, v1, v2, vcc
	v_mul_i32_i24_e32 v152, 0xd00, v2
	v_lshl_add_u64 v[2:3], v[152:153], 1, v[16:17]
	v_mov_b32_e32 v2, v88
	v_mov_b32_e32 v3, v89
	v_mov_b32_e32 v4, v90
	v_mov_b32_e32 v5, v91
	s_waitcnt vmcnt(0)
	v_cndmask_b32_e32 v23, 0, v2, vcc
	v_add_u32_e32 v2, 4, v0
	v_cndmask_b32_e32 v20, 0, v5, vcc
	v_cndmask_b32_e32 v21, 0, v4, vcc
	v_cndmask_b32_e32 v22, 0, v3, vcc
	v_cmp_gt_u32_e32 vcc, s37, v2
	s_and_b64 vcc, s[40:41], vcc
	s_nop 0
	v_cndmask_b32_e32 v2, v1, v2, vcc
	v_mul_i32_i24_e32 v152, 0xd00, v2
	v_lshl_add_u64 v[2:3], v[152:153], 1, v[16:17]
	v_mov_b32_e32 v2, v92
	v_mov_b32_e32 v3, v93
	v_mov_b32_e32 v4, v94
	v_mov_b32_e32 v5, v95
	s_waitcnt vmcnt(0)
	v_cndmask_b32_e32 v26, 0, v3, vcc
	v_cndmask_b32_e32 v27, 0, v2, vcc
	v_lshlrev_b32_e32 v2, 16, v8
	v_and_b32_e32 v3, 0xffff0000, v8
	v_cndmask_b32_e32 v24, 0, v5, vcc
	v_cndmask_b32_e32 v25, 0, v4, vcc
	v_pk_add_f32 v[2:3], v[2:3], 0 op_sel_hi:[1,0]
	v_lshlrev_b32_e32 v4, 16, v10
	v_and_b32_e32 v5, 0xffff0000, v10
	v_pk_add_f32 v[2:3], v[2:3], v[4:5]
	v_lshlrev_b32_e32 v4, 16, v11
	v_and_b32_e32 v5, 0xffff0000, v11
	v_pk_add_f32 v[2:3], v[2:3], v[4:5]
	v_lshlrev_b32_e32 v4, 16, v23
	v_and_b32_e32 v5, 0xffff0000, v23
	v_pk_add_f32 v[2:3], v[2:3], v[4:5]
	v_lshlrev_b32_e32 v4, 16, v27
	v_and_b32_e32 v5, 0xffff0000, v27
	v_pk_add_f32 v[10:11], v[2:3], v[4:5]
	v_lshlrev_b32_e32 v2, 16, v7
	v_and_b32_e32 v3, 0xffff0000, v7
	v_pk_add_f32 v[2:3], v[2:3], 0 op_sel_hi:[1,0]
	v_lshlrev_b32_e32 v4, 16, v9
	v_and_b32_e32 v5, 0xffff0000, v9
	v_pk_add_f32 v[2:3], v[2:3], v[4:5]
	v_lshlrev_b32_e32 v4, 16, v19
	v_and_b32_e32 v5, 0xffff0000, v19
	v_pk_add_f32 v[2:3], v[2:3], v[4:5]
	v_lshlrev_b32_e32 v4, 16, v22
	v_and_b32_e32 v5, 0xffff0000, v22
	v_pk_add_f32 v[2:3], v[2:3], v[4:5]
	v_lshlrev_b32_e32 v4, 16, v26
	v_and_b32_e32 v5, 0xffff0000, v26
	v_pk_add_f32 v[8:9], v[2:3], v[4:5]
	v_lshlrev_b32_e32 v2, 16, v6
	v_and_b32_e32 v3, 0xffff0000, v6
	v_pk_add_f32 v[2:3], v[2:3], 0 op_sel_hi:[1,0]
	v_lshlrev_b32_e32 v4, 16, v14
	v_and_b32_e32 v5, 0xffff0000, v14
	v_pk_add_f32 v[2:3], v[2:3], v[4:5]
	v_lshlrev_b32_e32 v4, 16, v18
	v_and_b32_e32 v5, 0xffff0000, v18
	v_pk_add_f32 v[2:3], v[2:3], v[4:5]
	v_lshlrev_b32_e32 v4, 16, v21
	v_and_b32_e32 v5, 0xffff0000, v21
	v_pk_add_f32 v[2:3], v[2:3], v[4:5]
	v_lshlrev_b32_e32 v4, 16, v25
	v_and_b32_e32 v5, 0xffff0000, v25
	v_pk_add_f32 v[6:7], v[2:3], v[4:5]
	v_lshlrev_b32_e32 v2, 16, v12
	v_and_b32_e32 v3, 0xffff0000, v12
	v_pk_add_f32 v[2:3], v[2:3], 0 op_sel_hi:[1,0]
	v_lshlrev_b32_e32 v4, 16, v13
	v_and_b32_e32 v5, 0xffff0000, v13
	v_pk_add_f32 v[2:3], v[2:3], v[4:5]
	v_lshlrev_b32_e32 v4, 16, v15
	v_and_b32_e32 v5, 0xffff0000, v15
	v_pk_add_f32 v[2:3], v[2:3], v[4:5]
	v_lshlrev_b32_e32 v4, 16, v20
	v_and_b32_e32 v5, 0xffff0000, v20
	v_pk_add_f32 v[2:3], v[2:3], v[4:5]
	v_lshlrev_b32_e32 v4, 16, v24
	v_and_b32_e32 v5, 0xffff0000, v24
	v_pk_add_f32 v[4:5], v[2:3], v[4:5]
	v_add_u32_e32 v2, 5, v0
	v_cmp_gt_u32_e32 vcc, s37, v2
	s_and_b64 vcc, s[40:41], vcc
	s_nop 0
	v_cndmask_b32_e32 v2, v1, v2, vcc
	v_mul_i32_i24_e32 v152, 0xd00, v2
	v_lshl_add_u64 v[2:3], v[152:153], 1, v[16:17]
	v_mov_b32_e32 v12, v96
	v_mov_b32_e32 v13, v97
	v_mov_b32_e32 v14, v98
	v_mov_b32_e32 v15, v99
	s_waitcnt vmcnt(0)
	v_cndmask_b32_e32 v2, 0, v15, vcc
	v_cndmask_b32_e32 v13, 0, v13, vcc
	v_cndmask_b32_e32 v12, 0, v12, vcc
	v_lshlrev_b32_e32 v20, 16, v12
	v_and_b32_e32 v21, 0xffff0000, v12
	v_lshlrev_b32_e32 v18, 16, v13
	v_and_b32_e32 v19, 0xffff0000, v13
	v_lshlrev_b32_e32 v12, 16, v2
	v_and_b32_e32 v13, 0xffff0000, v2
	v_add_u32_e32 v2, 6, v0
	v_cndmask_b32_e32 v3, 0, v14, vcc
	v_cmp_gt_u32_e32 vcc, s37, v2
	s_and_b64 vcc, s[40:41], vcc
	v_lshlrev_b32_e32 v14, 16, v3
	v_cndmask_b32_e32 v2, v1, v2, vcc
	v_mul_i32_i24_e32 v152, 0xd00, v2
	v_and_b32_e32 v15, 0xffff0000, v3
	v_lshl_add_u64 v[2:3], v[152:153], 1, v[16:17]
	v_mov_b32_e32 v22, v100
	v_mov_b32_e32 v23, v101
	v_mov_b32_e32 v24, v102
	v_mov_b32_e32 v25, v103
	v_pk_add_f32 v[8:9], v[8:9], v[18:19]
	v_pk_add_f32 v[6:7], v[6:7], v[14:15]
	v_pk_add_f32 v[4:5], v[4:5], v[12:13]
	s_waitcnt vmcnt(0)
	v_cndmask_b32_e32 v2, 0, v25, vcc
	v_cndmask_b32_e32 v23, 0, v23, vcc
	v_cndmask_b32_e32 v22, 0, v22, vcc
	v_lshlrev_b32_e32 v32, 16, v22
	v_and_b32_e32 v33, 0xffff0000, v22
	v_lshlrev_b32_e32 v28, 16, v23
	v_and_b32_e32 v29, 0xffff0000, v23
	v_lshlrev_b32_e32 v22, 16, v2
	v_and_b32_e32 v23, 0xffff0000, v2
	v_add_u32_e32 v2, 7, v0
	v_cndmask_b32_e32 v3, 0, v24, vcc
	v_cmp_gt_u32_e32 vcc, s37, v2
	s_and_b64 vcc, s[40:41], vcc
	v_lshlrev_b32_e32 v24, 16, v3
	v_cndmask_b32_e32 v2, v1, v2, vcc
	v_mul_i32_i24_e32 v152, 0xd00, v2
	v_and_b32_e32 v25, 0xffff0000, v3
	v_lshl_add_u64 v[2:3], v[152:153], 1, v[16:17]
	v_mov_b32_e32 v34, v104
	v_mov_b32_e32 v35, v105
	v_mov_b32_e32 v36, v106
	v_mov_b32_e32 v37, v107
	v_pk_add_f32 v[8:9], v[8:9], v[28:29]
	v_pk_add_f32 v[6:7], v[6:7], v[24:25]
	v_pk_add_f32 v[4:5], v[4:5], v[22:23]
	s_waitcnt vmcnt(0)
	v_cndmask_b32_e32 v2, 0, v37, vcc
	v_cndmask_b32_e32 v26, 0, v35, vcc
	v_cndmask_b32_e32 v27, 0, v34, vcc
	v_cndmask_b32_e32 v3, 0, v36, vcc
	v_lshlrev_b32_e32 v36, 16, v27
	v_and_b32_e32 v37, 0xffff0000, v27
	v_lshlrev_b32_e32 v34, 16, v26
	v_and_b32_e32 v35, 0xffff0000, v26
	v_lshlrev_b32_e32 v26, 16, v2
	v_and_b32_e32 v27, 0xffff0000, v2
	v_add_u32_e32 v2, 8, v0
	v_cndmask_b32_e64 v2, v1, v2, s[42:43]
	v_mul_i32_i24_e32 v152, 0xd00, v2
	v_lshlrev_b32_e32 v30, 16, v3
	v_and_b32_e32 v31, 0xffff0000, v3
	v_lshl_add_u64 v[2:3], v[152:153], 1, v[16:17]
	v_mov_b32_e32 v44, v108
	v_mov_b32_e32 v45, v109
	v_mov_b32_e32 v46, v110
	v_mov_b32_e32 v47, v111
	v_add_u32_e32 v2, 9, v0
	v_cndmask_b32_e64 v2, v1, v2, s[42:43]
	v_mul_i32_i24_e32 v152, 0xd00, v2
	v_lshl_add_u64 v[2:3], v[152:153], 1, v[16:17]
	v_mov_b32_e32 v48, v112
	v_mov_b32_e32 v49, v113
	v_mov_b32_e32 v50, v114
	v_mov_b32_e32 v51, v115
	v_add_u32_e32 v2, 10, v0
	v_cndmask_b32_e64 v2, v1, v2, s[42:43]
	v_mul_i32_i24_e32 v152, 0xd00, v2
	v_lshl_add_u64 v[2:3], v[152:153], 1, v[16:17]
	v_mov_b32_e32 v56, v116
	v_mov_b32_e32 v57, v117
	v_mov_b32_e32 v58, v118
	v_mov_b32_e32 v59, v119
	v_add_u32_e32 v2, 11, v0
	v_cndmask_b32_e64 v2, v1, v2, s[42:43]
	v_mul_i32_i24_e32 v152, 0xd00, v2
	v_lshl_add_u64 v[2:3], v[152:153], 1, v[16:17]
	v_pk_add_f32 v[8:9], v[8:9], v[34:35]
	v_pk_add_f32 v[6:7], v[6:7], v[30:31]
	v_pk_add_f32 v[4:5], v[4:5], v[26:27]
	s_waitcnt vmcnt(2)
	v_cndmask_b32_e64 v40, 0, v47, s[42:43]
	v_cndmask_b32_e64 v42, 0, v46, s[42:43]
	v_cndmask_b32_e64 v46, 0, v45, s[42:43]
	v_cndmask_b32_e64 v53, 0, v44, s[42:43]
	v_lshlrev_b32_e32 v14, 16, v42
	s_waitcnt vmcnt(1)
	v_cndmask_b32_e64 v41, 0, v51, s[42:43]
	v_cndmask_b32_e64 v62, 0, v48, s[42:43]
	v_cndmask_b32_e64 v44, 0, v50, s[42:43]
	v_cndmask_b32_e64 v50, 0, v49, s[42:43]
	v_and_b32_e32 v15, 0xffff0000, v42
	s_waitcnt vmcnt(0)
	v_cndmask_b32_e64 v43, 0, v59, s[42:43]
	v_cndmask_b32_e64 v47, 0, v58, s[42:43]
	v_cndmask_b32_e64 v54, 0, v57, s[42:43]
	v_cndmask_b32_e64 v63, 0, v56, s[42:43]
	v_mov_b32_e32 v56, v120
	v_mov_b32_e32 v57, v121
	v_mov_b32_e32 v58, v122
	v_mov_b32_e32 v59, v123
	v_mov_b32_e32 v143, 0
	v_lshl_add_u64 v[144:145], s[16:17], 0, v[154:155]
	v_add_co_u32_e32 v144, vcc, 0xa400000, v144
	s_nop 1
	v_addc_co_u32_e32 v145, vcc, 0, v145, vcc
	s_add_i32 s21, s1, s18
	s_add_i32 s21, s21, 4
	v_mov_b32_e32 v141, s21
	global_load_dwordx4 v[76:79], v[144:145], off offset:1536
	v_add_u32_e32 v140, s18, v38
	v_add_u32_e32 v140, 4, v140
	v_cmp_gt_u32_e32 vcc, s37, v140
	s_nop 1
	v_cndmask_b32_e32 v140, v141, v140, vcc
	v_mul_lo_u32 v142, v140, s55
	v_lshl_add_u64 v[146:147], v[142:143], 1, v[16:17]
	global_load_dwordx4 v[80:83], v[146:147], off offset:1536
	v_add_u32_e32 v140, s18, v39
	v_add_u32_e32 v140, 4, v140
	v_cmp_gt_i32_e32 vcc, 0, v140
	s_nop 1
	v_cndmask_b32_e32 v140, v140, v141, vcc
	v_mul_lo_u32 v148, v140, s55
	v_ashrrev_i32_e32 v149, 31, v148
	v_lshl_add_u64 v[146:147], v[148:149], 1, v[16:17]
	global_load_dwordx4 v[84:87], v[146:147], off offset:1536
	s_add_i32 s21, s1, s18
	s_add_i32 s21, s21, 5
	v_mov_b32_e32 v141, s21
	v_add_co_u32_e32 v146, vcc, 0x1a00, v144
	s_nop 1
	v_addc_co_u32_e32 v147, vcc, 0, v145, vcc
	global_load_dwordx4 v[88:91], v[146:147], off offset:1536
	v_add_u32_e32 v140, s18, v38
	v_add_u32_e32 v140, 5, v140
	v_cmp_gt_u32_e32 vcc, s37, v140
	s_nop 1
	v_cndmask_b32_e32 v140, v141, v140, vcc
	v_mul_lo_u32 v142, v140, s55
	v_lshl_add_u64 v[146:147], v[142:143], 1, v[16:17]
	global_load_dwordx4 v[92:95], v[146:147], off offset:1536
	v_add_u32_e32 v140, s18, v39
	v_add_u32_e32 v140, 5, v140
	v_cmp_gt_i32_e32 vcc, 0, v140
	s_nop 1
	v_cndmask_b32_e32 v140, v140, v141, vcc
	v_mul_lo_u32 v148, v140, s55
	v_ashrrev_i32_e32 v149, 31, v148
	v_lshl_add_u64 v[146:147], v[148:149], 1, v[16:17]
	global_load_dwordx4 v[96:99], v[146:147], off offset:1536
	s_add_i32 s21, s1, s18
	s_add_i32 s21, s21, 6
	v_mov_b32_e32 v141, s21
	v_add_co_u32_e32 v146, vcc, 0x3400, v144
	s_nop 1
	v_addc_co_u32_e32 v147, vcc, 0, v145, vcc
	global_load_dwordx4 v[100:103], v[146:147], off offset:1536
	v_add_u32_e32 v140, s18, v38
	v_add_u32_e32 v140, 6, v140
	v_cmp_gt_u32_e32 vcc, s37, v140
	s_nop 1
	v_cndmask_b32_e32 v140, v141, v140, vcc
	v_mul_lo_u32 v142, v140, s55
	v_lshl_add_u64 v[146:147], v[142:143], 1, v[16:17]
	global_load_dwordx4 v[104:107], v[146:147], off offset:1536
	v_add_u32_e32 v140, s18, v39
	v_add_u32_e32 v140, 6, v140
	v_cmp_gt_i32_e32 vcc, 0, v140
	s_nop 1
	v_cndmask_b32_e32 v140, v140, v141, vcc
	v_mul_lo_u32 v148, v140, s55
	v_ashrrev_i32_e32 v149, 31, v148
	v_lshl_add_u64 v[146:147], v[148:149], 1, v[16:17]
	global_load_dwordx4 v[108:111], v[146:147], off offset:1536
	s_add_i32 s21, s1, s18
	s_add_i32 s21, s21, 7
	v_mov_b32_e32 v141, s21
	v_add_co_u32_e32 v146, vcc, 0x4e00, v144
	s_nop 1
	v_addc_co_u32_e32 v147, vcc, 0, v145, vcc
	global_load_dwordx4 v[112:115], v[146:147], off offset:1536
	v_add_u32_e32 v140, s18, v38
	v_add_u32_e32 v140, 7, v140
	v_cmp_gt_u32_e32 vcc, s37, v140
	s_nop 1
	v_cndmask_b32_e32 v140, v141, v140, vcc
	v_mul_lo_u32 v142, v140, s55
	v_lshl_add_u64 v[146:147], v[142:143], 1, v[16:17]
	global_load_dwordx4 v[116:119], v[146:147], off offset:1536
	v_add_u32_e32 v140, s18, v39
	v_add_u32_e32 v140, 7, v140
	v_cmp_gt_i32_e32 vcc, 0, v140
	s_nop 1
	v_cndmask_b32_e32 v140, v140, v141, vcc
	v_mul_lo_u32 v148, v140, s55
	v_ashrrev_i32_e32 v149, 31, v148
	v_lshl_add_u64 v[146:147], v[148:149], 1, v[16:17]
	global_load_dwordx4 v[120:123], v[146:147], off offset:1536
	v_add_u32_e32 v2, 12, v0
	v_cndmask_b32_e64 v2, v1, v2, s[42:43]
	v_mul_i32_i24_e32 v152, 0xd00, v2
	v_lshl_add_u64 v[2:3], v[152:153], 1, v[16:17]
	v_lshlrev_b32_e32 v12, 16, v40
	v_and_b32_e32 v13, 0xffff0000, v40
	v_pk_add_f32 v[6:7], v[6:7], v[14:15]
	v_lshlrev_b32_e32 v14, 16, v44
	v_and_b32_e32 v15, 0xffff0000, v44
	v_pk_add_f32 v[4:5], v[4:5], v[12:13]
	v_lshlrev_b32_e32 v12, 16, v41
	v_and_b32_e32 v13, 0xffff0000, v41
	v_pk_add_f32 v[6:7], v[6:7], v[14:15]
	v_lshlrev_b32_e32 v14, 16, v47
	v_and_b32_e32 v15, 0xffff0000, v47
	v_pk_add_f32 v[4:5], v[4:5], v[12:13]
	v_lshlrev_b32_e32 v12, 16, v43
	v_and_b32_e32 v13, 0xffff0000, v43
	v_pk_add_f32 v[6:7], v[6:7], v[14:15]
	v_pk_add_f32 v[4:5], v[4:5], v[12:13]
	v_cndmask_b32_e64 v45, 0, v59, s[42:43]
	v_cndmask_b32_e64 v51, 0, v58, s[42:43]
	v_cndmask_b32_e64 v64, 0, v57, s[42:43]
	v_cndmask_b32_e64 v65, 0, v56, s[42:43]
	v_mov_b32_e32 v56, v124
	v_mov_b32_e32 v57, v125
	v_mov_b32_e32 v58, v126
	v_mov_b32_e32 v59, v127
	v_add_u32_e32 v2, 13, v0
	v_cndmask_b32_e64 v2, v1, v2, s[42:43]
	v_mul_i32_i24_e32 v152, 0xd00, v2
	v_lshl_add_u64 v[2:3], v[152:153], 1, v[16:17]
	v_lshlrev_b32_e32 v14, 16, v51
	v_and_b32_e32 v15, 0xffff0000, v51
	v_lshlrev_b32_e32 v12, 16, v45
	v_and_b32_e32 v13, 0xffff0000, v45
	v_pk_add_f32 v[6:7], v[6:7], v[14:15]
	v_pk_add_f32 v[4:5], v[4:5], v[12:13]
	v_cndmask_b32_e64 v48, 0, v59, s[42:43]
	v_cndmask_b32_e64 v55, 0, v58, s[42:43]
	v_mov_b32_e32 v58, v128
	v_mov_b32_e32 v59, v129
	v_mov_b32_e32 v60, v130
	v_mov_b32_e32 v61, v131
	v_add_u32_e32 v2, 14, v0
	v_cndmask_b32_e64 v2, v1, v2, s[42:43]
	v_add_u32_e32 v0, 15, v0
	v_mul_i32_i24_e32 v152, 0xd00, v2
	v_cndmask_b32_e64 v0, v1, v0, s[42:43]
	v_lshl_add_u64 v[2:3], v[152:153], 1, v[16:17]
	v_mul_i32_i24_e32 v152, 0xd00, v0
	v_lshl_add_u64 v[0:1], v[152:153], 1, v[16:17]
	v_cndmask_b32_e64 v66, 0, v56, s[42:43]
	v_cndmask_b32_e64 v57, 0, v57, s[42:43]
	v_lshlrev_b32_e32 v14, 16, v55
	v_and_b32_e32 v15, 0xffff0000, v55
	v_lshlrev_b32_e32 v12, 16, v48
	v_and_b32_e32 v13, 0xffff0000, v48
	v_pk_add_f32 v[6:7], v[6:7], v[14:15]
	v_pk_add_f32 v[4:5], v[4:5], v[12:13]
	v_cndmask_b32_e64 v49, 0, v61, s[42:43]
	v_cndmask_b32_e64 v56, 0, v60, s[42:43]
	v_cndmask_b32_e64 v67, 0, v59, s[42:43]
	v_cndmask_b32_e64 v68, 0, v58, s[42:43]
	v_mov_b32_e32 v58, v132
	v_mov_b32_e32 v59, v133
	v_mov_b32_e32 v60, v134
	v_mov_b32_e32 v61, v135
	v_lshlrev_b32_e32 v14, 16, v56
	v_mov_b32_e32 v0, v136
	v_mov_b32_e32 v1, v137
	v_mov_b32_e32 v2, v138
	v_mov_b32_e32 v3, v139
	v_and_b32_e32 v15, 0xffff0000, v56
	v_lshlrev_b32_e32 v12, 16, v49
	v_and_b32_e32 v13, 0xffff0000, v49
	v_pk_add_f32 v[6:7], v[6:7], v[14:15]
	v_pk_add_f32 v[4:5], v[4:5], v[12:13]
	v_cndmask_b32_e64 v52, 0, v61, s[42:43]
	v_cndmask_b32_e64 v60, 0, v60, s[42:43]
	v_cndmask_b32_e64 v70, 0, v1, s[42:43]
	v_cndmask_b32_e64 v71, 0, v0, s[42:43]
	v_pk_add_f32 v[0:1], v[10:11], v[20:21]
	v_cndmask_b32_e64 v61, 0, v3, s[42:43]
	v_pk_add_f32 v[0:1], v[0:1], v[32:33]
	v_cndmask_b32_e64 v69, 0, v2, s[42:43]
	v_pk_add_f32 v[0:1], v[0:1], v[36:37]
	v_lshlrev_b32_e32 v2, 16, v53
	v_and_b32_e32 v3, 0xffff0000, v53
	v_lshlrev_b32_e32 v10, 16, v46
	v_and_b32_e32 v11, 0xffff0000, v46
	v_pk_add_f32 v[0:1], v[0:1], v[2:3]
	v_lshlrev_b32_e32 v2, 16, v62
	v_and_b32_e32 v3, 0xffff0000, v62
	v_pk_add_f32 v[8:9], v[8:9], v[10:11]
	v_lshlrev_b32_e32 v10, 16, v50
	v_and_b32_e32 v11, 0xffff0000, v50
	v_pk_add_f32 v[0:1], v[0:1], v[2:3]
	v_lshlrev_b32_e32 v2, 16, v63
	v_and_b32_e32 v3, 0xffff0000, v63
	v_pk_add_f32 v[8:9], v[8:9], v[10:11]
	v_lshlrev_b32_e32 v10, 16, v54
	v_and_b32_e32 v11, 0xffff0000, v54
	v_pk_add_f32 v[0:1], v[0:1], v[2:3]
	v_lshlrev_b32_e32 v2, 16, v65
	v_and_b32_e32 v3, 0xffff0000, v65
	v_pk_add_f32 v[8:9], v[8:9], v[10:11]
	v_lshlrev_b32_e32 v10, 16, v64
	v_and_b32_e32 v11, 0xffff0000, v64
	v_pk_add_f32 v[0:1], v[0:1], v[2:3]
	v_lshlrev_b32_e32 v2, 16, v66
	v_and_b32_e32 v3, 0xffff0000, v66
	v_pk_add_f32 v[8:9], v[8:9], v[10:11]
	v_lshlrev_b32_e32 v10, 16, v57
	v_and_b32_e32 v11, 0xffff0000, v57
	v_cndmask_b32_e64 v59, 0, v59, s[42:43]
	v_cndmask_b32_e64 v58, 0, v58, s[42:43]
	v_pk_add_f32 v[0:1], v[0:1], v[2:3]
	v_lshlrev_b32_e32 v2, 16, v68
	v_and_b32_e32 v3, 0xffff0000, v68
	v_pk_add_f32 v[8:9], v[8:9], v[10:11]
	v_lshlrev_b32_e32 v10, 16, v67
	v_and_b32_e32 v11, 0xffff0000, v67
	v_pk_add_f32 v[0:1], v[0:1], v[2:3]
	v_lshlrev_b32_e32 v2, 16, v58
	v_and_b32_e32 v3, 0xffff0000, v58
	v_pk_add_f32 v[8:9], v[8:9], v[10:11]
	v_lshlrev_b32_e32 v10, 16, v59
	v_and_b32_e32 v11, 0xffff0000, v59
	v_lshlrev_b32_e32 v14, 16, v60
	v_and_b32_e32 v15, 0xffff0000, v60
	v_lshlrev_b32_e32 v12, 16, v52
	v_and_b32_e32 v13, 0xffff0000, v52
	v_pk_add_f32 v[0:1], v[0:1], v[2:3]
	v_lshlrev_b32_e32 v2, 16, v71
	v_and_b32_e32 v3, 0xffff0000, v71
	v_pk_add_f32 v[8:9], v[8:9], v[10:11]
	v_lshlrev_b32_e32 v10, 16, v70
	v_and_b32_e32 v11, 0xffff0000, v70
	v_pk_add_f32 v[6:7], v[6:7], v[14:15]
	v_lshlrev_b32_e32 v14, 16, v69
	v_and_b32_e32 v15, 0xffff0000, v69
	v_pk_add_f32 v[4:5], v[4:5], v[12:13]
	v_lshlrev_b32_e32 v12, 16, v61
	v_and_b32_e32 v13, 0xffff0000, v61
	v_pk_add_f32 v[18:19], v[0:1], v[2:3]
	v_pk_add_f32 v[22:23], v[8:9], v[10:11]
	v_pk_add_f32 v[20:21], v[6:7], v[14:15]
	v_pk_add_f32 v[24:25], v[4:5], v[12:13]
.LBB0_613:
	s_waitcnt vmcnt(0)
	v_lshl_add_u64 v[28:29], s[16:17], 0, v[154:155]
	s_add_i32 s19, s1, s18
	v_add_u32_e32 v26, s18, v38
	v_add_co_u32_e32 v0, vcc, 0xa400000, v28
	s_add_i32 s20, s19, 4
	v_add_u32_e32 v72, 4, v26
	v_addc_co_u32_e32 v1, vcc, 0, v29, vcc
	v_cmp_gt_u32_e32 vcc, s37, v72
	v_mov_b32_e32 v4, s20
	v_mov_b32_e32 v12, v76
	v_mov_b32_e32 v13, v77
	v_mov_b32_e32 v14, v78
	v_mov_b32_e32 v15, v79
	v_cndmask_b32_e32 v0, v4, v72, vcc
	v_mul_lo_u32 v152, v0, s55
	v_lshl_add_u64 v[0:1], v[152:153], 1, v[16:17]
	v_mov_b32_e32 v0, v80
	v_mov_b32_e32 v1, v81
	v_mov_b32_e32 v2, v82
	v_mov_b32_e32 v3, v83
	v_add_u32_e32 v41, s18, v39
	v_add_u32_e32 v73, 4, v41
	s_mov_b32 s21, 0xa402000
	s_add_i32 s20, s19, 5
	v_add_u32_e32 v57, 5, v26
	v_mov_b32_e32 v8, s20
	v_add_u32_e32 v58, 5, v41
	s_add_i32 s20, s19, 6
	v_add_u32_e32 v62, 6, v26
	v_mov_b32_e32 v36, s20
	v_add_u32_e32 v63, 6, v41
	s_mov_b32 s20, 0xa405000
	s_add_i32 s19, s19, 7
	v_add_u32_e32 v65, 7, v26
	v_mov_b32_e32 v26, s19
	v_add_u32_e32 v66, 7, v41
	s_mov_b32 s19, 0x1d400000
	s_add_i32 s18, s18, 4
	s_waitcnt vmcnt(0)
	v_cndmask_b32_e32 v27, 0, v3, vcc
	v_cndmask_b32_e32 v32, 0, v2, vcc
	v_cndmask_b32_e32 v42, 0, v1, vcc
	v_cndmask_b32_e32 v47, 0, v0, vcc
	v_cmp_gt_i32_e32 vcc, 0, v73
	s_nop 1
	v_cndmask_b32_e32 v0, v73, v4, vcc
	v_mul_lo_u32 v0, v0, s55
	v_ashrrev_i32_e32 v1, 31, v0
	v_lshl_add_u64 v[0:1], v[0:1], 1, v[16:17]
	v_mov_b32_e32 v0, v84
	v_mov_b32_e32 v1, v85
	v_mov_b32_e32 v2, v86
	v_mov_b32_e32 v3, v87
	s_waitcnt vmcnt(0)
	v_cndmask_b32_e64 v30, v3, 0, vcc
	v_cndmask_b32_e64 v34, v2, 0, vcc
	v_cndmask_b32_e64 v45, v1, 0, vcc
	v_cndmask_b32_e64 v48, v0, 0, vcc
	v_add_co_u32_e32 v0, vcc, s21, v28
	s_mov_b32 s21, 0xa403000
	s_nop 0
	v_addc_co_u32_e32 v1, vcc, 0, v29, vcc
	v_cmp_gt_u32_e32 vcc, s37, v57
	v_mov_b32_e32 v0, v88
	v_mov_b32_e32 v1, v89
	v_mov_b32_e32 v2, v90
	v_mov_b32_e32 v3, v91
	s_nop 0
	v_cndmask_b32_e32 v4, v8, v57, vcc
	v_mul_lo_u32 v152, v4, s55
	v_lshl_add_u64 v[4:5], v[152:153], 1, v[16:17]
	v_mov_b32_e32 v4, v92
	v_mov_b32_e32 v5, v93
	v_mov_b32_e32 v6, v94
	v_mov_b32_e32 v7, v95
	s_waitcnt vmcnt(0)
	v_cndmask_b32_e32 v31, 0, v7, vcc
	v_cndmask_b32_e32 v37, 0, v6, vcc
	v_cndmask_b32_e32 v49, 0, v5, vcc
	v_cndmask_b32_e32 v55, 0, v4, vcc
	v_cmp_gt_i32_e32 vcc, 0, v58
	s_nop 1
	v_cndmask_b32_e32 v4, v58, v8, vcc
	v_mul_lo_u32 v4, v4, s55
	v_ashrrev_i32_e32 v5, 31, v4
	v_lshl_add_u64 v[4:5], v[4:5], 1, v[16:17]
	v_mov_b32_e32 v4, v96
	v_mov_b32_e32 v5, v97
	v_mov_b32_e32 v6, v98
	v_mov_b32_e32 v7, v99
	s_waitcnt vmcnt(0)
	v_cndmask_b32_e64 v33, v7, 0, vcc
	v_cndmask_b32_e64 v40, v6, 0, vcc
	v_cndmask_b32_e64 v51, v5, 0, vcc
	v_cndmask_b32_e64 v56, v4, 0, vcc
	v_add_co_u32_e32 v4, vcc, s21, v28
	s_nop 1
	v_addc_co_u32_e32 v5, vcc, 0, v29, vcc
	v_cmp_gt_u32_e32 vcc, s37, v62
	v_mov_b32_e32 v4, v100
	v_mov_b32_e32 v5, v101
	v_mov_b32_e32 v6, v102
	v_mov_b32_e32 v7, v103
	s_nop 0
	v_cndmask_b32_e32 v8, v36, v62, vcc
	v_mul_lo_u32 v152, v8, s55
	v_lshl_add_u64 v[8:9], v[152:153], 1, v[16:17]
	v_mov_b32_e32 v8, v104
	v_mov_b32_e32 v9, v105
	v_mov_b32_e32 v10, v106
	v_mov_b32_e32 v11, v107
	s_waitcnt vmcnt(0)
	v_cndmask_b32_e32 v35, 0, v11, vcc
	v_cndmask_b32_e32 v44, 0, v10, vcc
	v_cndmask_b32_e32 v53, 0, v9, vcc
	v_cndmask_b32_e32 v61, 0, v8, vcc
	v_cmp_gt_i32_e32 vcc, 0, v63
	s_nop 1
	v_cndmask_b32_e32 v8, v63, v36, vcc
	v_mul_lo_u32 v8, v8, s55
	v_ashrrev_i32_e32 v9, 31, v8
	v_lshl_add_u64 v[8:9], v[8:9], 1, v[16:17]
	v_mov_b32_e32 v8, v108
	v_mov_b32_e32 v9, v109
	v_mov_b32_e32 v10, v110
	v_mov_b32_e32 v11, v111
	s_waitcnt vmcnt(0)
	v_cndmask_b32_e64 v36, v11, 0, vcc
	v_cndmask_b32_e64 v46, v10, 0, vcc
	v_cndmask_b32_e64 v54, v9, 0, vcc
	v_cndmask_b32_e64 v64, v8, 0, vcc
	v_add_co_u32_e32 v8, vcc, s20, v28
	s_nop 1
	v_addc_co_u32_e32 v9, vcc, 0, v29, vcc
	v_cmp_gt_u32_e32 vcc, s37, v65
	v_mov_b32_e32 v8, v112
	v_mov_b32_e32 v9, v113
	v_mov_b32_e32 v10, v114
	v_mov_b32_e32 v11, v115
	s_nop 0
	v_cndmask_b32_e32 v28, v26, v65, vcc
	v_mul_lo_u32 v152, v28, s55
	v_lshl_add_u64 v[28:29], v[152:153], 1, v[16:17]
	v_mov_b32_e32 v68, v116
	v_mov_b32_e32 v69, v117
	v_mov_b32_e32 v70, v118
	v_mov_b32_e32 v71, v119
	s_waitcnt vmcnt(0)
	v_cndmask_b32_e32 v41, 0, v71, vcc
	v_cndmask_b32_e32 v50, 0, v70, vcc
	v_cndmask_b32_e32 v59, 0, v69, vcc
	v_cndmask_b32_e32 v67, 0, v68, vcc
	v_cmp_gt_i32_e32 vcc, 0, v66
	s_nop 1
	v_cndmask_b32_e32 v26, v66, v26, vcc
	v_mul_lo_u32 v28, v26, s55
	v_ashrrev_i32_e32 v29, 31, v28
	v_lshl_add_u64 v[28:29], v[28:29], 1, v[16:17]
	v_mov_b32_e32 v68, v120
	v_mov_b32_e32 v69, v121
	v_mov_b32_e32 v70, v122
	v_mov_b32_e32 v71, v123
	v_max_i32_e32 v26, 0, v73
	v_min_u32_e32 v28, 0x2000, v72
	v_sub_u32_e32 v26, v28, v26
	v_cvt_f32_i32_e32 v26, v26
	v_mov_b32_e32 v72, v20
	v_mov_b32_e32 v73, v24
	v_div_scale_f32 v28, s[20:21], v26, v26, 1.0
	v_rcp_f32_e32 v29, v28
	s_waitcnt vmcnt(0)
	v_cndmask_b32_e64 v60, v69, 0, vcc
	v_fma_f32 v69, -v28, v29, 1.0
	v_cndmask_b32_e64 v43, v71, 0, vcc
	v_cndmask_b32_e64 v52, v70, 0, vcc
	v_cndmask_b32_e64 v68, v68, 0, vcc
	s_cmp_lt_u32 s18, 12
	s_cbranch_scc0 .Lmy_pool_nopf
	v_mov_b32_e32 v143, 0
	v_lshl_add_u64 v[144:145], s[16:17], 0, v[154:155]
	v_add_co_u32_e32 v144, vcc, 0xa406800, v144
	s_nop 1
	v_addc_co_u32_e32 v145, vcc, 0, v145, vcc
	s_add_i32 s21, s1, s18
	s_add_i32 s21, s21, 4
	v_mov_b32_e32 v141, s21
	global_load_dwordx4 v[76:79], v[144:145], off offset:1536
	v_add_u32_e32 v140, s18, v38
	v_add_u32_e32 v140, 4, v140
	v_cmp_gt_u32_e32 vcc, s37, v140
	s_nop 1
	v_cndmask_b32_e32 v140, v141, v140, vcc
	v_mul_lo_u32 v142, v140, s55
	v_lshl_add_u64 v[146:147], v[142:143], 1, v[16:17]
	global_load_dwordx4 v[80:83], v[146:147], off offset:1536
	v_add_u32_e32 v140, s18, v39
	v_add_u32_e32 v140, 4, v140
	v_cmp_gt_i32_e32 vcc, 0, v140
	s_nop 1
	v_cndmask_b32_e32 v140, v140, v141, vcc
	v_mul_lo_u32 v148, v140, s55
	v_ashrrev_i32_e32 v149, 31, v148
	v_lshl_add_u64 v[146:147], v[148:149], 1, v[16:17]
	global_load_dwordx4 v[84:87], v[146:147], off offset:1536
	s_add_i32 s21, s1, s18
	s_add_i32 s21, s21, 5
	v_mov_b32_e32 v141, s21
	v_add_co_u32_e32 v146, vcc, 0x1a00, v144
	s_nop 1
	v_addc_co_u32_e32 v147, vcc, 0, v145, vcc
	global_load_dwordx4 v[88:91], v[146:147], off offset:1536
	v_add_u32_e32 v140, s18, v38
	v_add_u32_e32 v140, 5, v140
	v_cmp_gt_u32_e32 vcc, s37, v140
	s_nop 1
	v_cndmask_b32_e32 v140, v141, v140, vcc
	v_mul_lo_u32 v142, v140, s55
	v_lshl_add_u64 v[146:147], v[142:143], 1, v[16:17]
	global_load_dwordx4 v[92:95], v[146:147], off offset:1536
	v_add_u32_e32 v140, s18, v39
	v_add_u32_e32 v140, 5, v140
	v_cmp_gt_i32_e32 vcc, 0, v140
	s_nop 1
	v_cndmask_b32_e32 v140, v140, v141, vcc
	v_mul_lo_u32 v148, v140, s55
	v_ashrrev_i32_e32 v149, 31, v148
	v_lshl_add_u64 v[146:147], v[148:149], 1, v[16:17]
	global_load_dwordx4 v[96:99], v[146:147], off offset:1536
	s_add_i32 s21, s1, s18
	s_add_i32 s21, s21, 6
	v_mov_b32_e32 v141, s21
	v_add_co_u32_e32 v146, vcc, 0x3400, v144
	s_nop 1
	v_addc_co_u32_e32 v147, vcc, 0, v145, vcc
	global_load_dwordx4 v[100:103], v[146:147], off offset:1536
	v_add_u32_e32 v140, s18, v38
	v_add_u32_e32 v140, 6, v140
	v_cmp_gt_u32_e32 vcc, s37, v140
	s_nop 1
	v_cndmask_b32_e32 v140, v141, v140, vcc
	v_mul_lo_u32 v142, v140, s55
	v_lshl_add_u64 v[146:147], v[142:143], 1, v[16:17]
	global_load_dwordx4 v[104:107], v[146:147], off offset:1536
	v_add_u32_e32 v140, s18, v39
	v_add_u32_e32 v140, 6, v140
	v_cmp_gt_i32_e32 vcc, 0, v140
	s_nop 1
	v_cndmask_b32_e32 v140, v140, v141, vcc
	v_mul_lo_u32 v148, v140, s55
	v_ashrrev_i32_e32 v149, 31, v148
	v_lshl_add_u64 v[146:147], v[148:149], 1, v[16:17]
	global_load_dwordx4 v[108:111], v[146:147], off offset:1536
	s_add_i32 s21, s1, s18
	s_add_i32 s21, s21, 7
	v_mov_b32_e32 v141, s21
	v_add_co_u32_e32 v146, vcc, 0x4e00, v144
	s_nop 1
	v_addc_co_u32_e32 v147, vcc, 0, v145, vcc
	global_load_dwordx4 v[112:115], v[146:147], off offset:1536
	v_add_u32_e32 v140, s18, v38
	v_add_u32_e32 v140, 7, v140
	v_cmp_gt_u32_e32 vcc, s37, v140
	s_nop 1
	v_cndmask_b32_e32 v140, v141, v140, vcc
	v_mul_lo_u32 v142, v140, s55
	v_lshl_add_u64 v[146:147], v[142:143], 1, v[16:17]
	global_load_dwordx4 v[116:119], v[146:147], off offset:1536
	v_add_u32_e32 v140, s18, v39
	v_add_u32_e32 v140, 7, v140
	v_cmp_gt_i32_e32 vcc, 0, v140
	s_nop 1
	v_cndmask_b32_e32 v140, v140, v141, vcc
	v_mul_lo_u32 v148, v140, s55
	v_ashrrev_i32_e32 v149, 31, v148
	v_lshl_add_u64 v[146:147], v[148:149], 1, v[16:17]
	global_load_dwordx4 v[120:123], v[146:147], off offset:1536
.Lmy_pool_nopf:
	v_fmac_f32_e32 v29, v69, v29
	v_div_scale_f32 v69, vcc, 1.0, v26, 1.0
	v_mul_f32_e32 v70, v69, v29
	v_fma_f32 v71, -v28, v70, v69
	v_fmac_f32_e32 v70, v71, v29
	v_fma_f32 v28, -v28, v70, v69
	v_div_fmas_f32 v28, v28, v29, v70
	v_div_fixup_f32 v26, v28, v26, 1.0
	v_lshlrev_b32_e32 v29, 16, v13
	v_lshlrev_b32_e32 v28, 16, v12
	v_mov_b32_e32 v70, v18
	v_mov_b32_e32 v71, v22
	v_and_b32_e32 v13, 0xffff0000, v13
	v_and_b32_e32 v12, 0xffff0000, v12
	v_pk_fma_f32 v[28:29], v[70:71], v[26:27], v[28:29] op_sel_hi:[1,0,1] neg_lo:[0,0,1] neg_hi:[0,0,1]
	v_mov_b32_e32 v70, v19
	v_mov_b32_e32 v71, v23
	v_pk_fma_f32 v[12:13], v[70:71], v[26:27], v[12:13] op_sel_hi:[1,0,1] neg_lo:[0,0,1] neg_hi:[0,0,1]
	v_lshlrev_b32_e32 v71, 16, v15
	v_lshlrev_b32_e32 v70, 16, v14
	v_and_b32_e32 v15, 0xffff0000, v15
	v_and_b32_e32 v14, 0xffff0000, v14
	v_pk_fma_f32 v[70:71], v[72:73], v[26:27], v[70:71] op_sel_hi:[1,0,1] neg_lo:[0,0,1] neg_hi:[0,0,1]
	v_mov_b32_e32 v72, v21
	v_mov_b32_e32 v73, v25
	v_pk_fma_f32 v[14:15], v[72:73], v[26:27], v[14:15] op_sel_hi:[1,0,1] neg_lo:[0,0,1] neg_hi:[0,0,1]
	v_bfe_u32 v72, v13, 16, 1
	v_bfe_u32 v69, v14, 16, 1
	v_bfe_u32 v73, v12, 16, 1
	v_bfe_u32 v26, v15, 16, 1
	v_add3_u32 v12, v12, v73, s54
	v_add3_u32 v13, v13, v72, s54
	v_add3_u32 v14, v14, v69, s54
	v_bfe_u32 v69, v29, 16, 1
	v_bfe_u32 v72, v70, 16, 1
	v_bfe_u32 v73, v71, 16, 1
	v_add3_u32 v15, v15, v26, s54
	v_bfe_u32 v26, v28, 16, 1
	v_add3_u32 v71, v71, v73, s54
	v_add3_u32 v70, v70, v72, s54
	v_add3_u32 v29, v29, v69, s54
	v_add3_u32 v26, v28, v26, s54
	v_lshrrev_b32_e32 v28, 16, v29
	v_lshrrev_b32_e32 v29, 16, v70
	v_lshrrev_b32_e32 v69, 16, v71
	v_and_or_b32 v73, v15, s52, v69
	v_and_or_b32 v72, v14, s52, v29
	v_max_i32_e32 v14, 0, v58
	v_min_u32_e32 v15, 0x2000, v57
	v_sub_u32_e32 v14, v15, v14
	v_cvt_f32_i32_e32 v14, v14
	v_lshrrev_b32_e32 v26, 16, v26
	v_and_or_b32 v70, v12, s52, v26
	v_and_or_b32 v71, v13, s52, v28
	v_div_scale_f32 v15, s[20:21], v14, v14, 1.0
	v_rcp_f32_e32 v26, v15
	v_lshl_add_u64 v[12:13], s[10:11], 0, v[154:155]
	v_add_co_u32_e32 v12, vcc, s19, v12
	v_fma_f32 v28, -v15, v26, 1.0
	s_nop 0
	v_addc_co_u32_e32 v13, vcc, 0, v13, vcc
	v_fmac_f32_e32 v26, v28, v26
	v_div_scale_f32 v28, vcc, 1.0, v14, 1.0
	v_mul_f32_e32 v29, v28, v26
	v_fma_f32 v57, -v15, v29, v28
	v_fmac_f32_e32 v29, v57, v26
	v_fma_f32 v15, -v15, v29, v28
	v_div_fmas_f32 v15, v15, v26, v29
	v_div_fixup_f32 v14, v15, v14, 1.0
	v_max_i32_e32 v15, 0, v63
	v_min_u32_e32 v26, 0x2000, v62
	v_sub_u32_e32 v15, v26, v15
	v_cvt_f32_i32_e32 v15, v15
	global_store_dwordx4 v[12:13], v[70:73], off
	v_and_b32_e32 v63, 0xffff0000, v47
	v_and_b32_e32 v69, 0xffff0000, v45
	v_div_scale_f32 v26, s[20:21], v15, v15, 1.0
	v_rcp_f32_e32 v28, v26
	v_lshlrev_b32_e32 v70, 16, v48
	v_and_b32_e32 v71, 0xffff0000, v48
	v_lshlrev_b32_e32 v48, 16, v49
	v_fma_f32 v29, -v26, v28, 1.0
	v_fmac_f32_e32 v28, v29, v28
	v_div_scale_f32 v29, vcc, 1.0, v15, 1.0
	v_mul_f32_e32 v57, v29, v28
	v_fma_f32 v58, -v26, v57, v29
	v_fmac_f32_e32 v57, v58, v28
	v_fma_f32 v26, -v26, v57, v29
	v_div_fmas_f32 v26, v26, v28, v57
	v_div_fixup_f32 v26, v26, v15, 1.0
	v_max_i32_e32 v15, 0, v66
	v_min_u32_e32 v28, 0x2000, v65
	v_sub_u32_e32 v15, v28, v15
	v_cvt_f32_i32_e32 v15, v15
	v_lshlrev_b32_e32 v66, 16, v68
	v_and_b32_e32 v49, 0xffff0000, v49
	s_add_u32 s10, s10, 0x1000
	v_div_scale_f32 v28, s[20:21], v15, v15, 1.0
	v_rcp_f32_e32 v29, v28
	s_addc_u32 s11, s11, 0
	s_add_u32 s16, s16, 0x6800
	s_addc_u32 s17, s17, 0
	v_fma_f32 v57, -v28, v29, 1.0
	v_fmac_f32_e32 v29, v57, v29
	v_div_scale_f32 v57, vcc, 1.0, v15, 1.0
	v_mul_f32_e32 v58, v57, v29
	v_fma_f32 v62, -v28, v58, v57
	v_fmac_f32_e32 v58, v62, v29
	v_lshlrev_b32_e32 v62, 16, v47
	v_pk_add_f32 v[62:63], v[62:63], v[70:71] neg_lo:[0,1] neg_hi:[0,1]
	v_lshlrev_b32_e32 v70, 16, v56
	v_pk_add_f32 v[62:63], v[18:19], v[62:63]
	v_lshlrev_b32_e32 v18, 16, v55
	v_and_b32_e32 v19, 0xffff0000, v55
	v_and_b32_e32 v71, 0xffff0000, v56
	v_pk_add_f32 v[18:19], v[18:19], v[70:71] neg_lo:[0,1] neg_hi:[0,1]
	v_fma_f32 v28, -v28, v58, v57
	v_pk_add_f32 v[56:57], v[62:63], v[18:19]
	v_lshlrev_b32_e32 v18, 16, v61
	v_and_b32_e32 v19, 0xffff0000, v61
	v_lshlrev_b32_e32 v70, 16, v64
	v_and_b32_e32 v71, 0xffff0000, v64
	v_pk_add_f32 v[18:19], v[18:19], v[70:71] neg_lo:[0,1] neg_hi:[0,1]
	v_div_fmas_f32 v28, v28, v29, v58
	v_pk_add_f32 v[64:65], v[56:57], v[18:19]
	v_lshlrev_b32_e32 v18, 16, v67
	v_and_b32_e32 v19, 0xffff0000, v67
	v_and_b32_e32 v67, 0xffff0000, v68
	v_pk_add_f32 v[18:19], v[18:19], v[66:67] neg_lo:[0,1] neg_hi:[0,1]
	v_lshlrev_b32_e32 v66, 16, v42
	v_and_b32_e32 v67, 0xffff0000, v42
	v_lshlrev_b32_e32 v68, 16, v45
	v_pk_add_f32 v[66:67], v[66:67], v[68:69] neg_lo:[0,1] neg_hi:[0,1]
	v_mov_b32_e32 v68, v62
	v_pk_add_f32 v[22:23], v[22:23], v[66:67]
	v_lshlrev_b32_e32 v67, 16, v1
	v_lshlrev_b32_e32 v66, 16, v0
	v_and_b32_e32 v1, 0xffff0000, v1
	v_and_b32_e32 v0, 0xffff0000, v0
	v_mov_b32_e32 v62, v63
	v_mov_b32_e32 v63, v23
	v_pk_fma_f32 v[0:1], v[14:15], v[62:63], v[0:1] op_sel_hi:[0,1,1] neg_lo:[0,0,1] neg_hi:[0,0,1]
	v_lshlrev_b32_e32 v62, 16, v51
	v_and_b32_e32 v63, 0xffff0000, v51
	v_pk_add_f32 v[48:49], v[48:49], v[62:63] neg_lo:[0,1] neg_hi:[0,1]
	v_mov_b32_e32 v69, v22
	v_pk_add_f32 v[22:23], v[22:23], v[48:49]
	v_lshlrev_b32_e32 v49, 16, v5
	v_lshlrev_b32_e32 v48, 16, v4
	v_mov_b32_e32 v62, v56
	v_mov_b32_e32 v63, v22
	v_pk_fma_f32 v[48:49], v[26:27], v[62:63], v[48:49] op_sel_hi:[0,1,1] neg_lo:[0,0,1] neg_hi:[0,0,1]
	v_div_fixup_f32 v28, v28, v15, 1.0
	v_pk_fma_f32 v[66:67], v[14:15], v[68:69], v[66:67] op_sel_hi:[0,1,1] neg_lo:[0,0,1] neg_hi:[0,0,1]
	v_and_b32_e32 v5, 0xffff0000, v5
	v_and_b32_e32 v4, 0xffff0000, v4
	v_mov_b32_e32 v56, v57
	v_mov_b32_e32 v57, v23
	v_and_b32_sdwa v15, v49, v203 dst_sel:DWORD dst_unused:UNUSED_PAD src0_sel:WORD_1 src1_sel:DWORD
	v_and_b32_sdwa v29, v48, v203 dst_sel:DWORD dst_unused:UNUSED_PAD src0_sel:WORD_1 src1_sel:DWORD
	v_pk_fma_f32 v[4:5], v[26:27], v[56:57], v[4:5] op_sel_hi:[0,1,1] neg_lo:[0,0,1] neg_hi:[0,0,1]
	v_add3_u32 v29, v48, v29, s54
	v_add3_u32 v15, v49, v15, s54
	v_lshlrev_b32_e32 v48, 16, v53
	v_and_b32_e32 v49, 0xffff0000, v53
	v_lshlrev_b32_e32 v56, 16, v54
	v_and_b32_e32 v57, 0xffff0000, v54
	v_pk_add_f32 v[48:49], v[48:49], v[56:57] neg_lo:[0,1] neg_hi:[0,1]
	v_and_b32_sdwa v42, v5, v203 dst_sel:DWORD dst_unused:UNUSED_PAD src0_sel:WORD_1 src1_sel:DWORD
	v_and_b32_sdwa v45, v4, v203 dst_sel:DWORD dst_unused:UNUSED_PAD src0_sel:WORD_1 src1_sel:DWORD
	v_pk_add_f32 v[22:23], v[22:23], v[48:49]
	v_add3_u32 v5, v5, v42, s54
	v_add3_u32 v4, v4, v45, s54
	v_lshlrev_b32_e32 v49, 16, v9
	v_lshlrev_b32_e32 v48, 16, v8
	v_mov_b32_e32 v54, v64
	v_mov_b32_e32 v55, v22
	v_and_b32_e32 v5, 0xffff0000, v5
	v_and_b32_e32 v4, 0xffff0000, v4
	v_and_b32_e32 v9, 0xffff0000, v9
	v_and_b32_e32 v8, 0xffff0000, v8
	v_pk_fma_f32 v[48:49], v[28:29], v[54:55], v[48:49] op_sel_hi:[0,1,1] neg_lo:[0,0,1] neg_hi:[0,0,1]
	v_mov_b32_e32 v54, v65
	v_mov_b32_e32 v55, v23
	v_or_b32_sdwa v5, v5, v15 dst_sel:DWORD dst_unused:UNUSED_PAD src0_sel:DWORD src1_sel:WORD_1
	v_or_b32_sdwa v4, v4, v29 dst_sel:DWORD dst_unused:UNUSED_PAD src0_sel:DWORD src1_sel:WORD_1
	v_pk_fma_f32 v[8:9], v[28:29], v[54:55], v[8:9] op_sel_hi:[0,1,1] neg_lo:[0,0,1] neg_hi:[0,0,1]
	v_and_b32_sdwa v15, v49, v203 dst_sel:DWORD dst_unused:UNUSED_PAD src0_sel:WORD_1 src1_sel:DWORD
	v_and_b32_sdwa v29, v48, v203 dst_sel:DWORD dst_unused:UNUSED_PAD src0_sel:WORD_1 src1_sel:DWORD
	v_add3_u32 v29, v48, v29, s54
	v_add3_u32 v15, v49, v15, s54
	v_lshlrev_b32_e32 v48, 16, v59
	v_and_b32_e32 v49, 0xffff0000, v59
	v_lshlrev_b32_e32 v54, 16, v60
	v_and_b32_e32 v55, 0xffff0000, v60
	v_pk_add_f32 v[48:49], v[48:49], v[54:55] neg_lo:[0,1] neg_hi:[0,1]
	v_lshlrev_b32_e32 v54, 16, v34
	v_pk_add_f32 v[22:23], v[22:23], v[48:49]
	v_lshlrev_b32_e32 v48, 16, v32
	v_and_b32_e32 v49, 0xffff0000, v32
	v_and_b32_e32 v55, 0xffff0000, v34
	v_pk_add_f32 v[48:49], v[48:49], v[54:55] neg_lo:[0,1] neg_hi:[0,1]
	v_lshlrev_b32_e32 v54, 16, v40
	v_pk_add_f32 v[48:49], v[20:21], v[48:49]
	v_lshlrev_b32_e32 v20, 16, v37
	v_and_b32_e32 v21, 0xffff0000, v37
	v_and_b32_e32 v55, 0xffff0000, v40
	v_and_b32_sdwa v42, v9, v203 dst_sel:DWORD dst_unused:UNUSED_PAD src0_sel:WORD_1 src1_sel:DWORD
	v_pk_add_f32 v[20:21], v[20:21], v[54:55] neg_lo:[0,1] neg_hi:[0,1]
	v_add3_u32 v9, v9, v42, s54
	v_pk_add_f32 v[20:21], v[48:49], v[20:21]
	v_and_b32_e32 v55, 0xffff0000, v6
	v_lshlrev_b32_e32 v54, 16, v6
	v_and_b32_e32 v9, 0xffff0000, v9
	v_pk_fma_f32 v[54:55], v[26:27], v[20:21], v[54:55] op_sel_hi:[0,1,1] neg_lo:[0,0,1] neg_hi:[0,0,1]
	v_and_b32_sdwa v45, v8, v203 dst_sel:DWORD dst_unused:UNUSED_PAD src0_sel:WORD_1 src1_sel:DWORD
	v_or_b32_sdwa v9, v9, v15 dst_sel:DWORD dst_unused:UNUSED_PAD src0_sel:DWORD src1_sel:WORD_1
	v_and_b32_sdwa v6, v55, v203 dst_sel:DWORD dst_unused:UNUSED_PAD src0_sel:WORD_1 src1_sel:DWORD
	v_and_b32_sdwa v15, v54, v203 dst_sel:DWORD dst_unused:UNUSED_PAD src0_sel:WORD_1 src1_sel:DWORD
	v_add3_u32 v8, v8, v45, s54
	v_add3_u32 v6, v55, v6, s54
	v_add3_u32 v15, v54, v15, s54
	v_lshlrev_b32_e32 v54, 16, v44
	v_and_b32_e32 v55, 0xffff0000, v44
	v_lshlrev_b32_e32 v44, 16, v46
	v_and_b32_e32 v45, 0xffff0000, v46
	v_pk_add_f32 v[44:45], v[54:55], v[44:45] neg_lo:[0,1] neg_hi:[0,1]
	v_lshrrev_b32_e32 v15, 16, v15
	v_pk_add_f32 v[20:21], v[20:21], v[44:45]
	v_and_b32_e32 v45, 0xffff0000, v10
	v_lshlrev_b32_e32 v44, 16, v10
	v_pk_fma_f32 v[44:45], v[28:29], v[20:21], v[44:45] op_sel_hi:[0,1,1] neg_lo:[0,0,1] neg_hi:[0,0,1]
	v_and_or_b32 v6, v6, s52, v15
	v_and_b32_sdwa v10, v45, v203 dst_sel:DWORD dst_unused:UNUSED_PAD src0_sel:WORD_1 src1_sel:DWORD
	v_and_b32_sdwa v15, v44, v203 dst_sel:DWORD dst_unused:UNUSED_PAD src0_sel:WORD_1 src1_sel:DWORD
	v_add3_u32 v10, v45, v10, s54
	v_add3_u32 v15, v44, v15, s54
	v_lshlrev_b32_e32 v44, 16, v50
	v_and_b32_e32 v45, 0xffff0000, v50
	v_lshlrev_b32_e32 v46, 16, v52
	v_and_b32_e32 v47, 0xffff0000, v52
	v_pk_add_f32 v[44:45], v[44:45], v[46:47] neg_lo:[0,1] neg_hi:[0,1]
	v_lshlrev_b32_e32 v46, 16, v30
	v_pk_add_f32 v[20:21], v[20:21], v[44:45]
	v_lshlrev_b32_e32 v44, 16, v27
	v_and_b32_e32 v45, 0xffff0000, v27
	v_and_b32_e32 v47, 0xffff0000, v30
	v_pk_add_f32 v[44:45], v[44:45], v[46:47] neg_lo:[0,1] neg_hi:[0,1]
	v_lshrrev_b32_e32 v15, 16, v15
	v_pk_add_f32 v[24:25], v[24:25], v[44:45]
	v_lshlrev_b32_e32 v45, 16, v3
	v_lshlrev_b32_e32 v44, 16, v2
	v_mov_b32_e32 v46, v48
	v_mov_b32_e32 v47, v24
	v_and_b32_e32 v3, 0xffff0000, v3
	v_and_b32_e32 v2, 0xffff0000, v2
	v_pk_fma_f32 v[44:45], v[14:15], v[46:47], v[44:45] op_sel_hi:[0,1,1] neg_lo:[0,0,1] neg_hi:[0,0,1]
	v_mov_b32_e32 v46, v49
	v_mov_b32_e32 v47, v25
	v_and_or_b32 v10, v10, s52, v15
	v_pk_fma_f32 v[2:3], v[14:15], v[46:47], v[2:3] op_sel_hi:[0,1,1] neg_lo:[0,0,1] neg_hi:[0,0,1]
	v_lshlrev_b32_e32 v14, 16, v31
	v_and_b32_e32 v15, 0xffff0000, v31
	v_lshlrev_b32_e32 v30, 16, v33
	v_and_b32_e32 v31, 0xffff0000, v33
	v_pk_add_f32 v[14:15], v[14:15], v[30:31] neg_lo:[0,1] neg_hi:[0,1]
	v_and_b32_e32 v8, 0xffff0000, v8
	v_pk_add_f32 v[14:15], v[24:25], v[14:15]
	v_and_b32_e32 v25, 0xffff0000, v7
	v_lshlrev_b32_e32 v24, 16, v7
	v_pk_fma_f32 v[24:25], v[26:27], v[14:15], v[24:25] op_sel_hi:[0,1,1] neg_lo:[0,0,1] neg_hi:[0,0,1]
	v_and_b32_sdwa v26, v24, v203 dst_sel:DWORD dst_unused:UNUSED_PAD src0_sel:WORD_1 src1_sel:DWORD
	v_and_b32_sdwa v7, v25, v203 dst_sel:DWORD dst_unused:UNUSED_PAD src0_sel:WORD_1 src1_sel:DWORD
	v_add3_u32 v24, v24, v26, s54
	v_add3_u32 v7, v25, v7, s54
	v_lshrrev_b32_e32 v24, 16, v24
	v_and_or_b32 v7, v7, s52, v24
	v_lshlrev_b32_e32 v24, 16, v35
	v_and_b32_e32 v25, 0xffff0000, v35
	v_lshlrev_b32_e32 v26, 16, v36
	v_and_b32_e32 v27, 0xffff0000, v36
	v_pk_add_f32 v[24:25], v[24:25], v[26:27] neg_lo:[0,1] neg_hi:[0,1]
	v_or_b32_sdwa v8, v8, v29 dst_sel:DWORD dst_unused:UNUSED_PAD src0_sel:DWORD src1_sel:WORD_1
	v_pk_add_f32 v[14:15], v[14:15], v[24:25]
	v_and_b32_e32 v25, 0xffff0000, v11
	v_lshlrev_b32_e32 v24, 16, v11
	v_pk_fma_f32 v[24:25], v[28:29], v[14:15], v[24:25] op_sel_hi:[0,1,1] neg_lo:[0,0,1] neg_hi:[0,0,1]
	v_bfe_u32 v28, v3, 16, 1
	v_bfe_u32 v29, v2, 16, 1
	v_bfe_u32 v30, v1, 16, 1
	v_bfe_u32 v31, v0, 16, 1
	v_and_b32_sdwa v26, v24, v203 dst_sel:DWORD dst_unused:UNUSED_PAD src0_sel:WORD_1 src1_sel:DWORD
	v_add3_u32 v0, v0, v31, s54
	v_add3_u32 v1, v1, v30, s54
	v_add3_u32 v2, v2, v29, s54
	v_add3_u32 v3, v3, v28, s54
	v_bfe_u32 v28, v66, 16, 1
	v_bfe_u32 v29, v67, 16, 1
	v_bfe_u32 v30, v44, 16, 1
	v_bfe_u32 v31, v45, 16, 1
	v_and_b32_sdwa v11, v25, v203 dst_sel:DWORD dst_unused:UNUSED_PAD src0_sel:WORD_1 src1_sel:DWORD
	v_add3_u32 v24, v24, v26, s54
	v_add3_u32 v31, v45, v31, s54
	v_add3_u32 v30, v44, v30, s54
	v_add3_u32 v29, v67, v29, s54
	v_add3_u32 v28, v66, v28, s54
	v_add3_u32 v11, v25, v11, s54
	v_lshrrev_b32_e32 v24, 16, v24
	v_lshrrev_b32_e32 v28, 16, v28
	v_lshrrev_b32_e32 v29, 16, v29
	v_lshrrev_b32_e32 v30, 16, v30
	v_lshrrev_b32_e32 v31, 16, v31
	v_and_or_b32 v11, v11, s52, v24
	v_lshlrev_b32_e32 v24, 16, v41
	v_and_b32_e32 v25, 0xffff0000, v41
	v_lshlrev_b32_e32 v26, 16, v43
	v_and_b32_e32 v27, 0xffff0000, v43
	v_and_or_b32 v3, v3, s52, v31
	v_and_or_b32 v2, v2, s52, v30
	v_and_or_b32 v1, v1, s52, v29
	v_and_or_b32 v0, v0, s52, v28
	global_store_dwordx4 v[12:13], v[0:3], off offset:1024
	global_store_dwordx4 v[12:13], v[4:7], off offset:2048
	global_store_dwordx4 v[12:13], v[8:11], off offset:3072
	v_pk_add_f32 v[0:1], v[24:25], v[26:27] neg_lo:[0,1] neg_hi:[0,1]
	v_pk_add_f32 v[18:19], v[64:65], v[18:19]
	v_pk_add_f32 v[24:25], v[14:15], v[0:1]
	s_cmp_lt_u32 s18, 12
	s_cbranch_scc1 .LBB0_613
	v_readlane_b32 s1, v253, 50
	s_add_i32 s8, s8, s88
	s_add_i32 s0, s0, s1
	s_cmpk_lt_i32 s8, 0x800
	s_cbranch_scc1 .LBB0_612
